# DA: group 0 issues its LDS-DMA batch at the start of its MFMA block (one block earlier) instead of in the softmax block
# baseline (speedup 1.0000x reference)
.LBB0_598:
	v_add_f32_e32 v184, v18, v19
	v_lshlrev_b32_e32 v18, 1, v50
	v_and_b32_e32 v18, 32, v18
	v_and_or_b32 v18, v51, s66, v18
	v_and_b32_e32 v19, 0x100, v52
	v_fmac_f32_e32 v184, 0, v56
	v_or3_b32 v187, v18, v19, v53
	s_add_i32 s35, 0, 0xc000
	v_cmp_gt_u32_e64 s[4:5], 32, v50
	v_lshl_add_u32 v186, v54, 2, s18
	v_lshlrev_b32_e32 v185, 4, v55
	v_mov_b64_e32 v[32:33], v[16:17]
	v_mov_b64_e32 v[48:49], v[16:17]
	v_mov_b64_e32 v[64:65], v[16:17]
	s_mov_b32 s96, 1
	v_add_u32_e32 v193, s35, v187
	s_lshl_b32 s97, s12, 8
	s_mov_b32 s12, 0x8000
	s_movk_i32 s74, 0x4000
	s_mov_b32 s0, 0
	v_mov_b64_e32 v[30:31], v[14:15]
	v_mov_b64_e32 v[28:29], v[12:13]
	v_mov_b64_e32 v[26:27], v[10:11]
	v_mov_b64_e32 v[24:25], v[8:9]
	v_mov_b64_e32 v[22:23], v[6:7]
	v_mov_b64_e32 v[20:21], v[4:5]
	v_mov_b64_e32 v[18:19], v[2:3]
	v_mov_b64_e32 v[46:47], v[14:15]
	v_mov_b64_e32 v[44:45], v[12:13]
	v_mov_b64_e32 v[42:43], v[10:11]
	v_mov_b64_e32 v[40:41], v[8:9]
	v_mov_b64_e32 v[38:39], v[6:7]
	v_mov_b64_e32 v[36:37], v[4:5]
	v_mov_b64_e32 v[34:35], v[2:3]
	v_mov_b64_e32 v[62:63], v[14:15]
	v_mov_b64_e32 v[60:61], v[12:13]
	v_mov_b64_e32 v[58:59], v[10:11]
	v_mov_b64_e32 v[56:57], v[8:9]
	v_mov_b64_e32 v[54:55], v[6:7]
	v_mov_b64_e32 v[52:53], v[4:5]
	v_mov_b64_e32 v[50:51], v[2:3]
	s_mov_b32 s75, s74
	s_mov_b32 s74, s0
	v_add_u32_e32 v238, s74, v193
	v_mbcnt_lo_u32_b32 v242, -1, 0
	v_mbcnt_hi_u32_b32 v242, -1, v242
	v_and_b32_e32 v243, 7, v242
	v_lshrrev_b32_e32 v252, 4, v242
	v_lshrrev_b32_e32 v244, 3, v242
	v_xor_b32_e32 v244, v244, v252
	v_and_b32_e32 v244, 1, v244
	v_cmp_eq_u32_e64 s[100:101], 0, v244
	v_mov_b32_e32 v245, 0x3f803f80
	s_nop 1
	v_cndmask_b32_e64 v248, 0, v245, s[100:101]
	v_mov_b32_e32 v249, v248
	v_mov_b32_e32 v250, v248
	v_mov_b32_e32 v251, v248
	v_lshlrev_b32_e32 v252, 4, v252
	v_and_b32_e32 v244, 8, v242
	v_lshl_add_u32 v252, v244, 3, v252
	v_mov_b32_e32 v244, 0
	v_mov_b32_e32 v245, 0
	v_mov_b32_e32 v246, 0
	v_mov_b32_e32 v247, 0
	s_barrier
	s_setprio 3
	s_and_b64 vcc, exec, s[2:3]
	s_cbranch_vccnz .Lda_dmaP_skip
	s_mov_b32 m0, s93
	s_add_i32 s0, s94, s12
	global_load_lds_dwordx4 v150, s[58:59]
	s_add_u32 s58, s58, 0x100000
	s_addc_u32 s59, s59, 0
	s_add_i32 m0, s0, 0xc000
	s_nop 0
	global_load_lds_dwordx4 v170, s[60:61]
	s_add_i32 m0, s0, 0xc400
	s_add_u32 vcc_lo, s60, s24
	s_addc_u32 vcc_hi, s61, s25
	s_add_u32 s60, s60, 0x100000
	s_addc_u32 s61, s61, 0
	s_cmpk_lt_i32 s95, 0x84
	s_cselect_b32 s1, 0, -1
	s_cselect_b32 s0, 0, 0xffd00000
	global_load_lds_dwordx4 v172, vcc
	v_lshl_add_u64 v[254:255], v[174:175], 0, s[0:1]
	s_add_i32 s0, s97, 0
	s_add_i32 m0, s0, 0x18800
	v_lshl_add_u64 v[174:175], v[174:175], 0, s[20:21]
	global_load_lds_dword v[254:255], off
	s_add_i32 s95, s95, 1
.Lda_dmaP_skip:
	ds_read_b128 v[82:85], v188 offset:40960
	ds_read_b128 v[210:213], v188 offset:45056
	ds_read_b128 v[214:217], v189 offset:40960
	ds_read_b128 v[218:221], v189 offset:45056
	ds_read_b128 v[222:225], v190 offset:40960
	ds_read_b128 v[226:229], v190 offset:45056
	ds_read_b128 v[230:233], v191 offset:40960
	ds_read_b128 v[234:237], v191 offset:45056
	ds_read_b64_tr_b16 v[194:195], v238 offset:0
	ds_read_b64_tr_b16 v[196:197], v238 offset:0x800
	ds_read_b64_tr_b16 v[198:199], v238 offset:0x1000
	ds_read_b64_tr_b16 v[200:201], v238 offset:0x1800
	s_waitcnt lgkmcnt(11)
	v_mfma_f32_32x32x16_bf16 v[98:113], v[82:85], v[126:129], v[66:81]
	s_waitcnt lgkmcnt(10)
	v_mfma_f32_32x32x16_bf16 v[82:97], v[210:213], v[126:129], v[66:81]
	ds_read_b64_tr_b16 v[202:203], v238 offset:0x2000
	ds_read_b64_tr_b16 v[204:205], v238 offset:0x2800
	ds_read_b64_tr_b16 v[206:207], v238 offset:0x3000
	ds_read_b64_tr_b16 v[208:209], v238 offset:0x3800
	s_waitcnt lgkmcnt(13)
	v_mfma_f32_32x32x16_bf16 v[98:113], v[214:217], v[122:125], v[98:113]
	s_waitcnt lgkmcnt(12)
	v_mfma_f32_32x32x16_bf16 v[82:97], v[218:221], v[122:125], v[82:97]
	s_waitcnt lgkmcnt(11)
	v_mfma_f32_32x32x16_bf16 v[98:113], v[222:225], v[118:121], v[98:113]
	s_waitcnt lgkmcnt(10)
	v_mfma_f32_32x32x16_bf16 v[82:97], v[226:229], v[118:121], v[82:97]
	s_waitcnt lgkmcnt(9)
	v_mfma_f32_32x32x16_bf16 v[98:113], v[230:233], v[114:117], v[98:113]
	s_waitcnt lgkmcnt(8)
	v_mfma_f32_32x32x16_bf16 v[82:97], v[234:237], v[114:117], v[82:97]
	ds_read_b64_tr_b16 v[210:211], v238 offset:0x200
	ds_read_b64_tr_b16 v[212:213], v238 offset:0xa00
	ds_read_b64_tr_b16 v[214:215], v238 offset:0x1200
	ds_read_b64_tr_b16 v[216:217], v238 offset:0x1a00
	ds_read_b64_tr_b16 v[218:219], v238 offset:0x2200
	ds_read_b64_tr_b16 v[220:221], v238 offset:0x2a00
	ds_read_b64_tr_b16 v[222:223], v238 offset:0x3200
	ds_read_b64_tr_b16 v[224:225], v238 offset:0x3a00
	s_waitcnt lgkmcnt(14)
	v_mfma_f32_32x32x16_bf16 v[50:65], v[142:145], v[194:197], v[50:65]
	s_waitcnt lgkmcnt(12)
	v_mfma_f32_32x32x16_bf16 v[50:65], v[138:141], v[198:201], v[50:65]
	s_waitcnt lgkmcnt(10)
	v_mfma_f32_32x32x16_bf16 v[50:65], v[134:137], v[202:205], v[50:65]
	s_waitcnt lgkmcnt(8)
	v_mfma_f32_32x32x16_bf16 v[50:65], v[130:133], v[206:209], v[50:65]
	ds_read_b64_tr_b16 v[194:195], v238 offset:0x400
	ds_read_b64_tr_b16 v[196:197], v238 offset:0xc00
	ds_read_b64_tr_b16 v[198:199], v238 offset:0x1400
	ds_read_b64_tr_b16 v[200:201], v238 offset:0x1c00
	ds_read_b64_tr_b16 v[202:203], v238 offset:0x2400
	ds_read_b64_tr_b16 v[204:205], v238 offset:0x2c00
	ds_read_b64_tr_b16 v[206:207], v238 offset:0x3400
	ds_read_b64_tr_b16 v[208:209], v238 offset:0x3c00
	s_waitcnt lgkmcnt(14)
	v_mfma_f32_32x32x16_bf16 v[34:49], v[142:145], v[210:213], v[34:49]
	s_waitcnt lgkmcnt(12)
	v_mfma_f32_32x32x16_bf16 v[34:49], v[138:141], v[214:217], v[34:49]
	s_waitcnt lgkmcnt(10)
	v_mfma_f32_32x32x16_bf16 v[34:49], v[134:137], v[218:221], v[34:49]
	s_waitcnt lgkmcnt(8)
	v_mfma_f32_32x32x16_bf16 v[34:49], v[130:133], v[222:225], v[34:49]
	ds_read_b64_tr_b16 v[210:211], v238 offset:0x600
	ds_read_b64_tr_b16 v[212:213], v238 offset:0xe00
	ds_read_b64_tr_b16 v[214:215], v238 offset:0x1600
	ds_read_b64_tr_b16 v[216:217], v238 offset:0x1e00
	ds_read_b64_tr_b16 v[218:219], v238 offset:0x2600
	ds_read_b64_tr_b16 v[220:221], v238 offset:0x2e00
	ds_read_b64_tr_b16 v[222:223], v238 offset:0x3600
	ds_read_b64_tr_b16 v[224:225], v238 offset:0x3e00
	s_waitcnt lgkmcnt(14)
	v_mfma_f32_32x32x16_bf16 v[18:33], v[142:145], v[194:197], v[18:33]
	s_waitcnt lgkmcnt(12)
	v_mfma_f32_32x32x16_bf16 v[18:33], v[138:141], v[198:201], v[18:33]
	s_waitcnt lgkmcnt(10)
	v_mfma_f32_32x32x16_bf16 v[18:33], v[134:137], v[202:205], v[18:33]
	s_waitcnt lgkmcnt(8)
	v_mfma_f32_32x32x16_bf16 v[18:33], v[130:133], v[206:209], v[18:33]
	s_waitcnt lgkmcnt(6)
	v_mfma_f32_32x32x16_bf16 v[2:17], v[142:145], v[210:213], v[2:17]
	s_waitcnt lgkmcnt(4)
	v_mfma_f32_32x32x16_bf16 v[2:17], v[138:141], v[214:217], v[2:17]
	s_waitcnt lgkmcnt(2)
	v_mfma_f32_32x32x16_bf16 v[2:17], v[134:137], v[218:221], v[2:17]
	s_waitcnt lgkmcnt(0)
	v_mfma_f32_32x32x16_bf16 v[2:17], v[130:133], v[222:225], v[2:17]
	s_branch .Lda_after_ma
.LBB0_599:
	s_barrier
	s_setprio 3
	s_and_b64 vcc, exec, s[2:3]
	s_cbranch_vccnz .Lda_dmaA_skip
	s_mov_b32 m0, s93
	s_add_i32 s0, s94, s12
	global_load_lds_dwordx4 v150, s[58:59]
	s_add_u32 s58, s58, 0x100000
	s_addc_u32 s59, s59, 0
	s_add_i32 m0, s0, 0xc000
	s_nop 0
	global_load_lds_dwordx4 v170, s[60:61]
	s_add_i32 m0, s0, 0xc400
	s_add_u32 vcc_lo, s60, s24
	s_addc_u32 vcc_hi, s61, s25
	s_add_u32 s60, s60, 0x100000
	s_addc_u32 s61, s61, 0
	s_cmpk_lt_i32 s95, 0x84
	s_cselect_b32 s1, 0, -1
	s_cselect_b32 s0, 0, 0xffd00000
	global_load_lds_dwordx4 v172, vcc
	v_lshl_add_u64 v[254:255], v[174:175], 0, s[0:1]
	s_add_i32 s0, s97, 0
	s_add_i32 m0, s0, 0x18800
	v_lshl_add_u64 v[174:175], v[174:175], 0, s[20:21]
	global_load_lds_dword v[254:255], off
	s_add_i32 s95, s95, 1
.Lda_dmaA_skip:
	ds_read_b64_tr_b16 v[194:195], v238 offset:0
	ds_read_b64_tr_b16 v[196:197], v238 offset:0x800
	ds_read_b64_tr_b16 v[198:199], v238 offset:0x200
	ds_read_b64_tr_b16 v[200:201], v238 offset:0xa00
	ds_read_b64_tr_b16 v[202:203], v238 offset:0x400
	ds_read_b64_tr_b16 v[204:205], v238 offset:0xc00
	ds_read_b64_tr_b16 v[206:207], v238 offset:0x600
	ds_read_b64_tr_b16 v[208:209], v238 offset:0xe00
	ds_read_b128 v[226:229], v188 offset:45056
	ds_read_b128 v[230:233], v189 offset:40960
	ds_read_b128 v[234:237], v189 offset:45056
	s_waitcnt lgkmcnt(9)
	v_mfma_f32_32x32x16_bf16 v[50:65], v[142:145], v[194:197], v[50:65]
	ds_read_b64_tr_b16 v[210:211], v238 offset:0x1000
	ds_read_b64_tr_b16 v[212:213], v238 offset:0x1800
	s_waitcnt lgkmcnt(9)
	v_mfma_f32_32x32x16_bf16 v[34:49], v[142:145], v[198:201], v[34:49]
	ds_read_b64_tr_b16 v[214:215], v238 offset:0x1200
	ds_read_b64_tr_b16 v[216:217], v238 offset:0x1a00
	s_waitcnt lgkmcnt(9)
	v_mfma_f32_32x32x16_bf16 v[18:33], v[142:145], v[202:205], v[18:33]
	ds_read_b64_tr_b16 v[218:219], v238 offset:0x1400
	ds_read_b64_tr_b16 v[220:221], v238 offset:0x1c00
	s_waitcnt lgkmcnt(9)
	v_mfma_f32_32x32x16_bf16 v[2:17], v[142:145], v[206:209], v[2:17]
	ds_read_b64_tr_b16 v[222:223], v238 offset:0x1600
	ds_read_b64_tr_b16 v[224:225], v238 offset:0x1e00
	v_mfma_f32_16x16x32_bf16 v[244:247], v[142:145], v[248:251], v[244:247]
	s_waitcnt lgkmcnt(6)
	v_mfma_f32_32x32x16_bf16 v[50:65], v[138:141], v[210:213], v[50:65]
	ds_read_b64_tr_b16 v[194:195], v238 offset:0x2000
	ds_read_b64_tr_b16 v[196:197], v238 offset:0x2800
	s_waitcnt lgkmcnt(6)
	v_mfma_f32_32x32x16_bf16 v[34:49], v[138:141], v[214:217], v[34:49]
	ds_read_b64_tr_b16 v[198:199], v238 offset:0x2200
	ds_read_b64_tr_b16 v[200:201], v238 offset:0x2a00
	s_waitcnt lgkmcnt(6)
	v_mfma_f32_32x32x16_bf16 v[18:33], v[138:141], v[218:221], v[18:33]
	ds_read_b64_tr_b16 v[202:203], v238 offset:0x2400
	ds_read_b64_tr_b16 v[204:205], v238 offset:0x2c00
	s_waitcnt lgkmcnt(6)
	v_mfma_f32_32x32x16_bf16 v[2:17], v[138:141], v[222:225], v[2:17]
	ds_read_b64_tr_b16 v[206:207], v238 offset:0x2600
	ds_read_b64_tr_b16 v[208:209], v238 offset:0x2e00
	v_mfma_f32_16x16x32_bf16 v[244:247], v[138:141], v[248:251], v[244:247]
	s_waitcnt lgkmcnt(6)
	v_mfma_f32_32x32x16_bf16 v[50:65], v[134:137], v[194:197], v[50:65]
	ds_read_b64_tr_b16 v[210:211], v238 offset:0x3000
	ds_read_b64_tr_b16 v[212:213], v238 offset:0x3800
	s_waitcnt lgkmcnt(6)
	v_mfma_f32_32x32x16_bf16 v[34:49], v[134:137], v[198:201], v[34:49]
	ds_read_b64_tr_b16 v[214:215], v238 offset:0x3200
	ds_read_b64_tr_b16 v[216:217], v238 offset:0x3a00
	s_waitcnt lgkmcnt(6)
	v_mfma_f32_32x32x16_bf16 v[18:33], v[134:137], v[202:205], v[18:33]
	ds_read_b64_tr_b16 v[218:219], v238 offset:0x3400
	ds_read_b64_tr_b16 v[220:221], v238 offset:0x3c00
	s_waitcnt lgkmcnt(6)
	v_mfma_f32_32x32x16_bf16 v[2:17], v[134:137], v[206:209], v[2:17]
	ds_read_b64_tr_b16 v[222:223], v238 offset:0x3600
	ds_read_b64_tr_b16 v[224:225], v238 offset:0x3e00
	v_mfma_f32_16x16x32_bf16 v[244:247], v[134:137], v[248:251], v[244:247]
	s_waitcnt lgkmcnt(6)
	v_mfma_f32_32x32x16_bf16 v[50:65], v[130:133], v[210:213], v[50:65]
	ds_read_b128 v[82:85], v188 offset:40960
	ds_read_b128 v[194:197], v190 offset:40960
	s_waitcnt lgkmcnt(6)
	v_mfma_f32_32x32x16_bf16 v[34:49], v[130:133], v[214:217], v[34:49]
	ds_read_b128 v[198:201], v190 offset:45056
	s_waitcnt lgkmcnt(5)
	v_mfma_f32_32x32x16_bf16 v[18:33], v[130:133], v[218:221], v[18:33]
	ds_read_b128 v[202:205], v191 offset:40960
	s_waitcnt lgkmcnt(4)
	v_mfma_f32_32x32x16_bf16 v[2:17], v[130:133], v[222:225], v[2:17]
	ds_read_b128 v[206:209], v191 offset:45056
	v_mfma_f32_16x16x32_bf16 v[244:247], v[130:133], v[248:251], v[244:247]
	s_waitcnt lgkmcnt(4)
	v_mfma_f32_32x32x16_bf16 v[98:113], v[82:85], v[126:129], v[66:81]
	v_mfma_f32_32x32x16_bf16 v[82:97], v[226:229], v[126:129], v[66:81]
	v_mfma_f32_32x32x16_bf16 v[98:113], v[230:233], v[122:125], v[98:113]
	v_mfma_f32_32x32x16_bf16 v[82:97], v[234:237], v[122:125], v[82:97]
	s_waitcnt lgkmcnt(3)
	v_mfma_f32_32x32x16_bf16 v[98:113], v[194:197], v[118:121], v[98:113]
	s_waitcnt lgkmcnt(2)
	v_mfma_f32_32x32x16_bf16 v[82:97], v[198:201], v[118:121], v[82:97]
	s_waitcnt lgkmcnt(1)
	v_mfma_f32_32x32x16_bf16 v[98:113], v[202:205], v[114:117], v[98:113]
	s_waitcnt lgkmcnt(0)
	v_mfma_f32_32x32x16_bf16 v[82:97], v[206:209], v[114:117], v[82:97]

.LBB0_601:
	s_and_b64 vcc, exec, s[2:3]
	s_barrier
	s_setprio 0
.LBB0_603:
	s_and_b64 vcc, exec, s[6:7]
	s_cbranch_vccnz .LBB0_605
	s_add_i32 m0, s92, 0xa000
	s_add_i32 s0, s94, s74
	global_load_lds_dwordx4 v150, s[58:59]
	s_add_u32 s58, s58, 0x100000
	s_addc_u32 s59, s59, 0
	s_add_i32 m0, s0, 0xc000
	s_nop 0
	global_load_lds_dwordx4 v170, s[60:61]
	s_add_i32 m0, s0, 0xc400
	s_add_u32 vcc_lo, s60, s24
	s_addc_u32 vcc_hi, s61, s25
	s_add_u32 s60, s60, 0x100000
	s_addc_u32 s61, s61, 0
	s_cmpk_lt_i32 s95, 0x84
	s_cselect_b32 s1, 0, -1
	s_cselect_b32 s0, 0, 0xffd00000
	global_load_lds_dwordx4 v172, vcc
	v_lshl_add_u64 v[130:131], v[174:175], 0, s[0:1]
	s_add_i32 s0, s97, 0
	s_add_i32 m0, s0, 0x18800
	v_lshl_add_u64 v[174:175], v[174:175], 0, s[20:21]
	global_load_lds_dword v[130:131], off
	s_add_i32 s95, s95, 1

.LBB0_612:
	s_barrier
	s_setprio 3
	s_and_b64 vcc, exec, s[2:3]
	s_cbranch_vccnz .Lda_dmaB_skip
	s_add_i32 m0, s92, 0xa000
	s_add_i32 s0, s94, s74
	global_load_lds_dwordx4 v150, s[58:59]
	s_add_u32 s58, s58, 0x100000
	s_addc_u32 s59, s59, 0
	s_add_i32 m0, s0, 0xc000
	s_nop 0
	global_load_lds_dwordx4 v170, s[60:61]
	s_add_i32 m0, s0, 0xc400
	s_add_u32 vcc_lo, s60, s24
	s_addc_u32 vcc_hi, s61, s25
	s_add_u32 s60, s60, 0x100000
	s_addc_u32 s61, s61, 0
	s_cmpk_lt_i32 s95, 0x84
	s_cselect_b32 s1, 0, -1
	s_cselect_b32 s0, 0, 0xffd00000
	global_load_lds_dwordx4 v172, vcc
	v_lshl_add_u64 v[254:255], v[174:175], 0, s[0:1]
	s_add_i32 s0, s97, 0
	s_add_i32 m0, s0, 0x18800
	v_lshl_add_u64 v[174:175], v[174:175], 0, s[20:21]
	global_load_lds_dword v[254:255], off
	s_add_i32 s95, s95, 1
.Lda_dmaB_skip:
	v_add_u32_e32 v197, s75, v193
	ds_read_b64_tr_b16 v[198:199], v197 offset:0
	ds_read_b64_tr_b16 v[200:201], v197 offset:0x800
	ds_read_b64_tr_b16 v[202:203], v197 offset:0x200
	ds_read_b64_tr_b16 v[204:205], v197 offset:0xa00
	ds_read_b64_tr_b16 v[206:207], v197 offset:0x400
	ds_read_b64_tr_b16 v[208:209], v197 offset:0xc00
	ds_read_b64_tr_b16 v[210:211], v197 offset:0x600
	ds_read_b64_tr_b16 v[212:213], v197 offset:0xe00
	ds_read_b128 v[230:233], v188 offset:36864
	ds_read_b128 v[234:237], v189 offset:32768
	ds_read_b128 v[238:241], v189 offset:36864
	s_waitcnt lgkmcnt(9)
	v_mfma_f32_32x32x16_bf16 v[50:65], v[142:145], v[198:201], v[50:65]
	ds_read_b64_tr_b16 v[214:215], v197 offset:0x1000
	ds_read_b64_tr_b16 v[216:217], v197 offset:0x1800
	s_waitcnt lgkmcnt(9)
	v_mfma_f32_32x32x16_bf16 v[34:49], v[142:145], v[202:205], v[34:49]
	ds_read_b64_tr_b16 v[218:219], v197 offset:0x1200
	ds_read_b64_tr_b16 v[220:221], v197 offset:0x1a00
	s_waitcnt lgkmcnt(9)
	v_mfma_f32_32x32x16_bf16 v[18:33], v[142:145], v[206:209], v[18:33]
	ds_read_b64_tr_b16 v[222:223], v197 offset:0x1400
	ds_read_b64_tr_b16 v[224:225], v197 offset:0x1c00
	s_waitcnt lgkmcnt(9)
	v_mfma_f32_32x32x16_bf16 v[2:17], v[142:145], v[210:213], v[2:17]
	ds_read_b64_tr_b16 v[226:227], v197 offset:0x1600
	ds_read_b64_tr_b16 v[228:229], v197 offset:0x1e00
	v_mfma_f32_16x16x32_bf16 v[244:247], v[142:145], v[248:251], v[244:247]
	s_waitcnt lgkmcnt(6)
	v_mfma_f32_32x32x16_bf16 v[50:65], v[138:141], v[214:217], v[50:65]
	ds_read_b64_tr_b16 v[198:199], v197 offset:0x2000
	ds_read_b64_tr_b16 v[200:201], v197 offset:0x2800
	s_waitcnt lgkmcnt(6)
	v_mfma_f32_32x32x16_bf16 v[34:49], v[138:141], v[218:221], v[34:49]
	ds_read_b64_tr_b16 v[202:203], v197 offset:0x2200
	ds_read_b64_tr_b16 v[204:205], v197 offset:0x2a00
	s_waitcnt lgkmcnt(6)
	v_mfma_f32_32x32x16_bf16 v[18:33], v[138:141], v[222:225], v[18:33]
	ds_read_b64_tr_b16 v[206:207], v197 offset:0x2400
	ds_read_b64_tr_b16 v[208:209], v197 offset:0x2c00
	s_waitcnt lgkmcnt(6)
	v_mfma_f32_32x32x16_bf16 v[2:17], v[138:141], v[226:229], v[2:17]
	ds_read_b64_tr_b16 v[210:211], v197 offset:0x2600
	ds_read_b64_tr_b16 v[212:213], v197 offset:0x2e00
	v_mfma_f32_16x16x32_bf16 v[244:247], v[138:141], v[248:251], v[244:247]
	s_waitcnt lgkmcnt(6)
	v_mfma_f32_32x32x16_bf16 v[50:65], v[134:137], v[198:201], v[50:65]
	ds_read_b64_tr_b16 v[214:215], v197 offset:0x3000
	ds_read_b64_tr_b16 v[216:217], v197 offset:0x3800
	s_waitcnt lgkmcnt(6)
	v_mfma_f32_32x32x16_bf16 v[34:49], v[134:137], v[202:205], v[34:49]
	ds_read_b64_tr_b16 v[218:219], v197 offset:0x3200
	ds_read_b64_tr_b16 v[220:221], v197 offset:0x3a00
	s_waitcnt lgkmcnt(6)
	v_mfma_f32_32x32x16_bf16 v[18:33], v[134:137], v[206:209], v[18:33]
	ds_read_b64_tr_b16 v[222:223], v197 offset:0x3400
	ds_read_b64_tr_b16 v[224:225], v197 offset:0x3c00
	s_waitcnt lgkmcnt(6)
	v_mfma_f32_32x32x16_bf16 v[2:17], v[134:137], v[210:213], v[2:17]
	ds_read_b64_tr_b16 v[226:227], v197 offset:0x3600
	ds_read_b64_tr_b16 v[228:229], v197 offset:0x3e00
	v_mfma_f32_16x16x32_bf16 v[244:247], v[134:137], v[248:251], v[244:247]
	s_waitcnt lgkmcnt(6)
	v_mfma_f32_32x32x16_bf16 v[50:65], v[130:133], v[214:217], v[50:65]
	ds_read_b128 v[82:85], v188 offset:32768
	ds_read_b128 v[198:201], v190 offset:32768
	s_waitcnt lgkmcnt(6)
	v_mfma_f32_32x32x16_bf16 v[34:49], v[130:133], v[218:221], v[34:49]
	ds_read_b128 v[202:205], v190 offset:36864
	s_waitcnt lgkmcnt(5)
	v_mfma_f32_32x32x16_bf16 v[18:33], v[130:133], v[222:225], v[18:33]
	ds_read_b128 v[206:209], v191 offset:32768
	s_waitcnt lgkmcnt(4)
	v_mfma_f32_32x32x16_bf16 v[2:17], v[130:133], v[226:229], v[2:17]
	ds_read_b128 v[210:213], v191 offset:36864
	v_mfma_f32_16x16x32_bf16 v[244:247], v[130:133], v[248:251], v[244:247]
	s_waitcnt lgkmcnt(4)
	v_mfma_f32_32x32x16_bf16 v[98:113], v[82:85], v[126:129], v[66:81]
	v_mfma_f32_32x32x16_bf16 v[82:97], v[230:233], v[126:129], v[66:81]
	v_mfma_f32_32x32x16_bf16 v[98:113], v[234:237], v[122:125], v[98:113]
	v_mfma_f32_32x32x16_bf16 v[82:97], v[238:241], v[122:125], v[82:97]
	s_waitcnt lgkmcnt(3)
	v_mfma_f32_32x32x16_bf16 v[98:113], v[198:201], v[118:121], v[98:113]
	s_waitcnt lgkmcnt(2)
	v_mfma_f32_32x32x16_bf16 v[82:97], v[202:205], v[118:121], v[82:97]
	s_waitcnt lgkmcnt(1)
	v_mfma_f32_32x32x16_bf16 v[98:113], v[206:209], v[114:117], v[98:113]
	s_waitcnt lgkmcnt(0)
	v_mfma_f32_32x32x16_bf16 v[82:97], v[210:213], v[114:117], v[82:97]
	s_and_b64 vcc, exec, s[6:7]
	s_cbranch_vccnz .LBB0_614
	s_waitcnt vmcnt(1)
.LBB0_614:
	s_and_b64 vcc, exec, s[2:3]
	s_barrier
	s_setprio 0
.LBB0_616:
	s_cmpk_gt_u32 s96, 0x80
	s_cselect_b64 s[0:1], -1, 0
	s_cmpk_lt_u32 s96, 0x81
	s_cselect_b64 s[62:63], -1, 0
	s_and_b64 s[62:63], s[56:57], s[62:63]
	s_andn2_b64 vcc, exec, s[62:63]
	s_cbranch_vccnz .LBB0_618
	s_mov_b32 m0, s93
	s_add_i32 s13, s94, s75
	global_load_lds_dwordx4 v150, s[58:59]
	s_add_u32 s58, s58, 0x100000
	s_addc_u32 s59, s59, 0
	s_add_i32 m0, s13, 0xc000
	s_nop 0
	global_load_lds_dwordx4 v170, s[60:61]
	s_add_i32 m0, s13, 0xc400
	s_add_u32 vcc_lo, s60, s24
	s_addc_u32 vcc_hi, s61, s25
	s_add_u32 s60, s60, 0x100000
	s_addc_u32 s61, s61, 0
	s_cmpk_lt_i32 s95, 0x84
	s_cselect_b32 s63, 0, -1
	s_cselect_b32 s62, 0, 0xffd00000
	s_add_i32 s13, s97, 0
	global_load_lds_dwordx4 v172, vcc
	v_lshl_add_u64 v[130:131], v[174:175], 0, s[62:63]
	s_add_i32 m0, s13, 0x18800
	v_lshl_add_u64 v[174:175], v[174:175], 0, s[20:21]
	global_load_lds_dword v[130:131], off
	s_add_i32 s95, s95, 1
